# GEMM phases: one static s_setprio 1 for waves 4-7 at phase entry, the 16 per-segment priority toggles in the K-loop removed
# speedup vs baseline: 1.0138x; 1.0138x over previous
.LBB0_129:
	s_andn2_b64 vcc, exec, s[0:1]
	s_cbranch_vccnz .LBB0_231
	v_bfe_i32 v2, v182, 27, 1
	v_lshlrev_b32_e32 v0, 4, v182
	v_lshrrev_b32_e32 v2, 22, v2
	v_add_u32_e32 v2, v0, v2
	v_and_b32_e32 v2, 0xfffffc00, v2
	v_sub_u32_e32 v2, v0, v2
	s_waitcnt vmcnt(0)
	v_ashrrev_i32_e32 v1, 31, v182
	v_lshrrev_b32_e32 v3, 4, v2
	v_lshrrev_b32_e32 v1, 26, v1
	v_bitop3_b32 v2, v3, v2, 32 bitop3:0x6c
	v_add_u32_e32 v1, v182, v1
	s_waitcnt vmcnt(17)
	v_ashrrev_i32_e32 v4, 31, v2
	v_ashrrev_i32_e32 v1, 6, v1
	v_lshrrev_b32_e32 v4, 26, v4
	v_lshlrev_b32_e32 v3, 3, v1
	v_add_u32_e32 v4, v2, v4
	v_and_b32_e32 v3, -16, v3
	v_ashrrev_i32_e32 v5, 6, v4
	v_lshlrev_b32_e32 v1, 5, v1
	v_add_u32_e32 v3, v5, v3
	v_and_b32_e32 v12, 32, v1
	v_and_b32_e32 v1, 0xc0, v4
	v_sub_u32_e32 v1, v2, v1
	v_lshlrev_b32_e32 v2, 1, v3
	v_lshrrev_b32_e32 v4, 2, v3
	v_and_b32_e32 v5, 3, v5
	s_mov_b32 s1, 0x7fffffe0
	v_ashrrev_i16_sdwa v1, v226, sext(v1) dst_sel:DWORD dst_unused:UNUSED_PAD src0_sel:DWORD src1_sel:BYTE_0
	v_and_b32_e32 v2, 24, v2
	v_and_b32_e32 v4, 4, v4
	v_and_or_b32 v5, v3, s1, v5
	v_bfe_i32 v13, v1, 0, 16
	v_or3_b32 v2, v5, v4, v2
	v_add_u32_e32 v1, v12, v13
	v_mul_lo_u32 v14, s7, v3
	v_mul_lo_u32 v2, s7, v2
	v_add_u32_e32 v0, 0x2000, v0
	v_add_lshl_u32 v184, v14, v1, 1
	v_add_lshl_u32 v186, v2, v1, 1
	v_ashrrev_i32_e32 v1, 31, v0
	v_lshrrev_b32_e32 v1, 22, v1
	v_add_u32_e32 v1, v0, v1
	v_ashrrev_i32_e32 v1, 10, v1
	v_mul_i32_i24_e32 v2, 0x400, v1
	v_sub_u32_e32 v0, v0, v2
	v_lshrrev_b32_e32 v2, 4, v0
	v_bitop3_b32 v0, v2, v0, 32 bitop3:0x6c
	v_ashrrev_i32_e32 v3, 31, v0
	s_lshl_b32 s98, s7, 8
	s_mov_b32 s99, s81
	v_lshrrev_b32_e32 v3, 26, v3
	s_lshl_b64 s[36:37], s[98:99], 1
	s_ashr_i32 s4, s19, 31
	v_lshlrev_b32_e32 v2, 3, v1
	v_add_u32_e32 v3, v0, v3
	s_mul_i32 s4, s36, s4
	s_mul_hi_u32 s5, s36, s19
	s_ashr_i32 s8, s18, 31
	v_and_b32_e32 v2, -16, v2
	v_ashrrev_i32_e32 v4, 6, v3
	s_add_i32 s4, s5, s4
	s_bfe_u32 s5, s7, 0x10017
	s_mul_i32 s8, s36, s8
	s_mul_hi_u32 s9, s36, s18
	s_ashr_i32 s0, s12, 6
	v_add_u32_e32 v2, v4, v2
	v_lshlrev_b32_e32 v1, 5, v1
	v_and_b32_e32 v4, 3, v4
	s_mul_i32 s6, s5, s19
	s_add_i32 s8, s9, s8
	s_mul_i32 s5, s5, s18
	v_and_b32_e32 v15, 32, v1
	v_and_b32_e32 v1, 0xc0, v3
	v_and_or_b32 v4, v2, s1, v4
	s_ashr_i32 s1, s12, 8
	s_lshl_b32 s33, s0, 10
	s_add_i32 s4, s4, s6
	s_add_i32 s8, s8, s5
	s_mul_i32 s5, s36, s18
	v_sub_u32_e32 v0, v0, v1
	v_lshlrev_b32_e32 v1, 1, v2
	v_lshrrev_b32_e32 v3, 2, v2
	s_add_u32 s68, s88, s5
	v_ashrrev_i16_sdwa v0, v226, sext(v0) dst_sel:DWORD dst_unused:UNUSED_PAD src0_sel:DWORD src1_sel:BYTE_0
	v_and_b32_e32 v1, 24, v1
	v_and_b32_e32 v3, 4, v3
	s_addc_u32 s69, s89, s8
	s_add_i32 s76, s33, 0
	v_bfe_i32 v16, v0, 0, 16
	v_or3_b32 v1, v4, v3, v1
	s_add_i32 m0, s76, 0x10000
	v_add_u32_e32 v0, v15, v16
	v_mul_lo_u32 v1, s7, v1
	s_mul_i32 s6, s36, s19
	global_load_lds_dwordx4 v186, s[68:69]
	s_add_i32 m0, s76, 0x12000
	v_add_lshl_u32 v190, v1, v0, 1
	s_add_u32 s70, s84, s6
	v_mul_lo_u32 v17, s7, v2
	global_load_lds_dwordx4 v190, s[68:69]
	s_addc_u32 s71, s85, s4
	s_mov_b32 m0, s76
	s_add_i32 s4, s76, 0x2000
	v_add_lshl_u32 v188, v17, v0, 1
	global_load_lds_dwordx4 v184, s[70:71]
	s_mov_b32 m0, s4
	s_add_u32 s8, s68, s98
	global_load_lds_dwordx4 v188, s[70:71]
	s_addc_u32 s9, s69, 0
	s_add_i32 m0, s76, 0x14000
	v_mov_b32_e32 v187, v180
	v_mov_b32_e32 v191, v180
	global_load_lds_dwordx4 v186, s[8:9]
	s_add_i32 m0, s76, 0x16000
	s_waitcnt vmcnt(0)
	v_lshl_add_u64 v[8:9], s[8:9], 0, v[186:187]
	v_lshl_add_u64 v[10:11], s[8:9], 0, v[190:191]
	global_load_lds_dwordx4 v190, s[8:9]
	s_add_u32 s8, s70, s98
	s_addc_u32 s9, s71, 0
	s_add_i32 s5, s76, 0x4000
	s_mov_b32 m0, s5
	s_add_i32 s6, s76, 0x6000
	global_load_lds_dwordx4 v184, s[8:9]
	s_mov_b32 m0, s6
	s_load_dword s74, s[24:25], 0x0
	global_load_lds_dwordx4 v188, s[8:9]
	v_mov_b32_e32 v185, v180
	v_mov_b32_e32 v189, v180
	v_lshl_add_u64 v[0:1], s[68:69], 0, v[186:187]
	v_lshl_add_u64 v[2:3], s[68:69], 0, v[190:191]
	v_lshl_add_u64 v[4:5], s[70:71], 0, v[184:185]
	v_lshl_add_u64 v[6:7], s[70:71], 0, v[188:189]
	s_cmp_lg_u32 s1, 1
	v_writelane_b32 v240, s12, 12
	s_cbranch_scc1 .LBB0_132
	s_setprio 1
	s_barrier

.LBB0_141:
	s_add_i32 s72, s40, 2
	s_add_u32 s68, s0, 0x80
	s_addc_u32 s41, s1, 0
	s_add_i32 s73, 0, 0x10000
	v_add_u32_e32 v140, s73, v183
	ds_read_b128 v[128:131], v140
	ds_read_b128 v[132:135], v140 offset:1024
	ds_read_b128 v[136:139], v140 offset:2048
	ds_read_b128 v[140:143], v140 offset:3072
	s_cmp_eq_u32 s10, s40
	s_cselect_b32 s40, s64, s68
	s_cselect_b32 s41, s65, s41
	s_cselect_b32 s69, s67, s71
	s_cselect_b32 s68, s66, s70
	v_lshl_add_u64 v[176:177], s[0:1], 0, v[192:193]
	s_add_i32 m0, s76, 0xc000
	ds_read_b128 v[144:147], v239
	ds_read_b128 v[148:151], v239 offset:1024
	ds_read_b128 v[152:155], v239 offset:2048
	ds_read_b128 v[156:159], v239 offset:3072
	ds_read_b128 v[160:163], v239 offset:4096
	ds_read_b128 v[164:167], v239 offset:5120
	ds_read_b128 v[168:171], v239 offset:6144
	ds_read_b128 v[172:175], v239 offset:7168
	global_load_lds_dwordx4 v[176:177], off
	v_lshl_add_u64 v[176:177], s[0:1], 0, v[194:195]
	s_add_i32 m0, s76, 0xe000
	s_nop 0
	global_load_lds_dwordx4 v[176:177], off
	s_waitcnt lgkmcnt(8)
	s_barrier
	s_waitcnt lgkmcnt(0)
	s_waitcnt lgkmcnt(0)
	v_mfma_f32_16x16x32_bf16 v[124:127], v[128:131], v[144:147], v[124:127]
	v_mfma_f32_16x16x32_bf16 v[116:119], v[136:139], v[144:147], v[116:119]
	v_mfma_f32_16x16x32_bf16 v[108:111], v[128:131], v[152:155], v[108:111]
	v_mfma_f32_16x16x32_bf16 v[100:103], v[136:139], v[152:155], v[100:103]
	v_mfma_f32_16x16x32_bf16 v[92:95], v[128:131], v[160:163], v[92:95]
	v_mfma_f32_16x16x32_bf16 v[84:87], v[136:139], v[160:163], v[84:87]
	v_mfma_f32_16x16x32_bf16 v[76:79], v[128:131], v[168:171], v[76:79]
	v_mfma_f32_16x16x32_bf16 v[68:71], v[136:139], v[168:171], v[68:71]
	v_mfma_f32_16x16x32_bf16 v[124:127], v[132:135], v[148:151], v[124:127]
	v_mfma_f32_16x16x32_bf16 v[116:119], v[140:143], v[148:151], v[116:119]
	v_mfma_f32_16x16x32_bf16 v[108:111], v[132:135], v[156:159], v[108:111]
	v_mfma_f32_16x16x32_bf16 v[100:103], v[140:143], v[156:159], v[100:103]
	v_mfma_f32_16x16x32_bf16 v[92:95], v[132:135], v[164:167], v[92:95]
	v_mfma_f32_16x16x32_bf16 v[84:87], v[140:143], v[164:167], v[84:87]
	v_mfma_f32_16x16x32_bf16 v[76:79], v[132:135], v[172:175], v[76:79]
	v_mfma_f32_16x16x32_bf16 v[68:71], v[140:143], v[172:175], v[68:71]
	s_barrier
	s_add_i32 s80, 0, 0x14000
	s_add_i32 s73, s73, s33
	v_add_u32_e32 v204, s80, v183
	v_lshl_add_u64 v[208:209], s[68:69], 0, v[186:187]
	s_mov_b32 m0, s73
	ds_read_b128 v[176:179], v204
	ds_read_b128 v[196:199], v204 offset:1024
	ds_read_b128 v[200:203], v204 offset:2048
	ds_read_b128 v[204:207], v204 offset:3072
	global_load_lds_dwordx4 v[208:209], off
	v_lshl_add_u64 v[210:211], s[68:69], 0, v[190:191]
	s_add_i32 m0, s73, 0x2000
	s_nop 0
	global_load_lds_dwordx4 v[210:211], off
	s_barrier
	s_waitcnt lgkmcnt(0)
	s_waitcnt lgkmcnt(0)
	v_mfma_f32_16x16x32_bf16 v[120:123], v[176:179], v[144:147], v[120:123]
	v_mfma_f32_16x16x32_bf16 v[112:115], v[200:203], v[144:147], v[112:115]
	v_mfma_f32_16x16x32_bf16 v[104:107], v[176:179], v[152:155], v[104:107]
	v_mfma_f32_16x16x32_bf16 v[96:99], v[200:203], v[152:155], v[96:99]
	v_mfma_f32_16x16x32_bf16 v[88:91], v[176:179], v[160:163], v[88:91]
	v_mfma_f32_16x16x32_bf16 v[80:83], v[200:203], v[160:163], v[80:83]
	v_mfma_f32_16x16x32_bf16 v[72:75], v[176:179], v[168:171], v[72:75]
	v_mfma_f32_16x16x32_bf16 v[64:67], v[200:203], v[168:171], v[64:67]
	v_mfma_f32_16x16x32_bf16 v[120:123], v[196:199], v[148:151], v[120:123]
	v_mfma_f32_16x16x32_bf16 v[112:115], v[204:207], v[148:151], v[112:115]
	v_mfma_f32_16x16x32_bf16 v[104:107], v[196:199], v[156:159], v[104:107]
	v_mfma_f32_16x16x32_bf16 v[96:99], v[204:207], v[156:159], v[96:99]
	v_mfma_f32_16x16x32_bf16 v[88:91], v[196:199], v[164:167], v[88:91]
	v_mfma_f32_16x16x32_bf16 v[80:83], v[204:207], v[164:167], v[80:83]
	v_mfma_f32_16x16x32_bf16 v[72:75], v[196:199], v[172:175], v[72:75]
	v_mfma_f32_16x16x32_bf16 v[64:67], v[204:207], v[172:175], v[64:67]
	s_mov_b32 m0, s76
	v_lshl_add_u64 v[212:213], s[40:41], 0, v[184:185]
	s_barrier
	ds_read_b128 v[144:147], v239 offset:16384
	ds_read_b128 v[148:151], v239 offset:17408
	ds_read_b128 v[152:155], v239 offset:18432
	ds_read_b128 v[156:159], v239 offset:19456
	ds_read_b128 v[160:163], v239 offset:20480
	ds_read_b128 v[164:167], v239 offset:21504
	ds_read_b128 v[168:171], v239 offset:22528
	ds_read_b128 v[172:175], v239 offset:23552
	global_load_lds_dwordx4 v[212:213], off
	v_lshl_add_u64 v[214:215], s[40:41], 0, v[188:189]
	s_mov_b32 m0, s4
	s_nop 0
	global_load_lds_dwordx4 v[214:215], off
	s_barrier
	s_waitcnt lgkmcnt(0)
	s_waitcnt lgkmcnt(0)
	v_mfma_f32_16x16x32_bf16 v[60:63], v[128:131], v[144:147], v[60:63]
	v_mfma_f32_16x16x32_bf16 v[52:55], v[136:139], v[144:147], v[52:55]
	v_mfma_f32_16x16x32_bf16 v[44:47], v[128:131], v[152:155], v[44:47]
	v_mfma_f32_16x16x32_bf16 v[36:39], v[136:139], v[152:155], v[36:39]
	v_mfma_f32_16x16x32_bf16 v[28:31], v[128:131], v[160:163], v[28:31]
	v_mfma_f32_16x16x32_bf16 v[20:23], v[136:139], v[160:163], v[20:23]
	v_mfma_f32_16x16x32_bf16 v[12:15], v[128:131], v[168:171], v[12:15]
	v_mfma_f32_16x16x32_bf16 v[4:7], v[136:139], v[168:171], v[4:7]
	v_mfma_f32_16x16x32_bf16 v[60:63], v[132:135], v[148:151], v[60:63]
	v_mfma_f32_16x16x32_bf16 v[52:55], v[140:143], v[148:151], v[52:55]
	v_mfma_f32_16x16x32_bf16 v[44:47], v[132:135], v[156:159], v[44:47]
	v_mfma_f32_16x16x32_bf16 v[36:39], v[140:143], v[156:159], v[36:39]
	v_mfma_f32_16x16x32_bf16 v[28:31], v[132:135], v[164:167], v[28:31]
	v_mfma_f32_16x16x32_bf16 v[20:23], v[140:143], v[164:167], v[20:23]
	v_mfma_f32_16x16x32_bf16 v[12:15], v[132:135], v[172:175], v[12:15]
	v_mfma_f32_16x16x32_bf16 v[4:7], v[140:143], v[172:175], v[4:7]
	s_barrier
	s_add_u32 s68, s68, s98
	s_addc_u32 s69, s69, 0
	s_add_i32 s73, s80, s33
	v_lshl_add_u64 v[216:217], s[68:69], 0, v[186:187]
	s_mov_b32 m0, s73
	v_lshl_add_u64 v[218:219], s[68:69], 0, v[190:191]
	global_load_lds_dwordx4 v[216:217], off
	s_add_i32 m0, s73, 0x2000
	s_nop 0
	global_load_lds_dwordx4 v[218:219], off
	s_waitcnt vmcnt(6)
	s_barrier
	v_mfma_f32_16x16x32_bf16 v[56:59], v[176:179], v[144:147], v[56:59]
	v_mfma_f32_16x16x32_bf16 v[48:51], v[200:203], v[144:147], v[48:51]
	v_mfma_f32_16x16x32_bf16 v[40:43], v[176:179], v[152:155], v[40:43]
	v_mfma_f32_16x16x32_bf16 v[32:35], v[200:203], v[152:155], v[32:35]
	v_mfma_f32_16x16x32_bf16 v[24:27], v[176:179], v[160:163], v[24:27]
	v_mfma_f32_16x16x32_bf16 v[16:19], v[200:203], v[160:163], v[16:19]
	v_mfma_f32_16x16x32_bf16 v[8:11], v[176:179], v[168:171], v[8:11]
	v_mfma_f32_16x16x32_bf16 v[0:3], v[200:203], v[168:171], v[0:3]
	v_mfma_f32_16x16x32_bf16 v[56:59], v[196:199], v[148:151], v[56:59]
	v_mfma_f32_16x16x32_bf16 v[48:51], v[204:207], v[148:151], v[48:51]
	v_mfma_f32_16x16x32_bf16 v[40:43], v[196:199], v[156:159], v[40:43]
	v_mfma_f32_16x16x32_bf16 v[32:35], v[204:207], v[156:159], v[32:35]
	v_mfma_f32_16x16x32_bf16 v[24:27], v[196:199], v[164:167], v[24:27]
	v_mfma_f32_16x16x32_bf16 v[16:19], v[204:207], v[164:167], v[16:19]
	v_mfma_f32_16x16x32_bf16 v[8:11], v[196:199], v[172:175], v[8:11]
	v_mfma_f32_16x16x32_bf16 v[0:3], v[204:207], v[172:175], v[0:3]
	s_add_i32 s68, 0, 0x18000
	v_add_u32_e32 v140, s68, v183
	s_barrier
	ds_read_b128 v[128:131], v140
	ds_read_b128 v[132:135], v140 offset:1024
	ds_read_b128 v[136:139], v140 offset:2048
	ds_read_b128 v[140:143], v140 offset:3072
	s_add_u32 s40, s40, s98
	s_addc_u32 s41, s41, 0
	s_mov_b32 m0, s5
	v_lshl_add_u64 v[176:177], s[40:41], 0, v[184:185]
	ds_read_b128 v[144:147], v239 offset:32768
	ds_read_b128 v[148:151], v239 offset:33792
	ds_read_b128 v[152:155], v239 offset:34816
	ds_read_b128 v[156:159], v239 offset:35840
	ds_read_b128 v[160:163], v239 offset:36864
	ds_read_b128 v[164:167], v239 offset:37888
	ds_read_b128 v[168:171], v239 offset:38912
	ds_read_b128 v[172:175], v239 offset:39936
	global_load_lds_dwordx4 v[176:177], off
	v_lshl_add_u64 v[176:177], s[40:41], 0, v[188:189]
	s_mov_b32 m0, s6
	s_nop 0
	global_load_lds_dwordx4 v[176:177], off
	s_waitcnt lgkmcnt(8)
	s_barrier
	s_waitcnt lgkmcnt(0)
	s_waitcnt lgkmcnt(0)
	v_mfma_f32_16x16x32_bf16 v[124:127], v[128:131], v[144:147], v[124:127]
	v_mfma_f32_16x16x32_bf16 v[116:119], v[136:139], v[144:147], v[116:119]
	v_mfma_f32_16x16x32_bf16 v[108:111], v[128:131], v[152:155], v[108:111]
	v_mfma_f32_16x16x32_bf16 v[100:103], v[136:139], v[152:155], v[100:103]
	v_mfma_f32_16x16x32_bf16 v[92:95], v[128:131], v[160:163], v[92:95]
	v_mfma_f32_16x16x32_bf16 v[84:87], v[136:139], v[160:163], v[84:87]
	v_mfma_f32_16x16x32_bf16 v[76:79], v[128:131], v[168:171], v[76:79]
	v_mfma_f32_16x16x32_bf16 v[68:71], v[136:139], v[168:171], v[68:71]
	v_mfma_f32_16x16x32_bf16 v[124:127], v[132:135], v[148:151], v[124:127]
	v_mfma_f32_16x16x32_bf16 v[116:119], v[140:143], v[148:151], v[116:119]
	v_mfma_f32_16x16x32_bf16 v[108:111], v[132:135], v[156:159], v[108:111]
	v_mfma_f32_16x16x32_bf16 v[100:103], v[140:143], v[156:159], v[100:103]
	v_mfma_f32_16x16x32_bf16 v[92:95], v[132:135], v[164:167], v[92:95]
	v_mfma_f32_16x16x32_bf16 v[84:87], v[140:143], v[164:167], v[84:87]
	v_mfma_f32_16x16x32_bf16 v[76:79], v[132:135], v[172:175], v[76:79]
	v_mfma_f32_16x16x32_bf16 v[68:71], v[140:143], v[172:175], v[68:71]
	s_barrier
	s_add_i32 s40, 0, 0x1c000
	s_add_i32 s41, s68, s33
	v_add_u32_e32 v204, s40, v183
	v_lshl_add_u64 v[208:209], v[208:209], 0, s[96:97]
	s_mov_b32 m0, s41
	ds_read_b128 v[176:179], v204
	ds_read_b128 v[196:199], v204 offset:1024
	ds_read_b128 v[200:203], v204 offset:2048
	ds_read_b128 v[204:207], v204 offset:3072
	global_load_lds_dwordx4 v[208:209], off
	v_lshl_add_u64 v[208:209], v[210:211], 0, s[96:97]
	s_add_i32 m0, s41, 0x2000
	s_nop 0
	global_load_lds_dwordx4 v[208:209], off
	s_barrier
	s_waitcnt lgkmcnt(0)
	s_waitcnt lgkmcnt(0)
	v_mfma_f32_16x16x32_bf16 v[120:123], v[176:179], v[144:147], v[120:123]
	v_mfma_f32_16x16x32_bf16 v[112:115], v[200:203], v[144:147], v[112:115]
	v_mfma_f32_16x16x32_bf16 v[104:107], v[176:179], v[152:155], v[104:107]
	v_mfma_f32_16x16x32_bf16 v[96:99], v[200:203], v[152:155], v[96:99]
	v_mfma_f32_16x16x32_bf16 v[88:91], v[176:179], v[160:163], v[88:91]
	v_mfma_f32_16x16x32_bf16 v[80:83], v[200:203], v[160:163], v[80:83]
	v_mfma_f32_16x16x32_bf16 v[72:75], v[176:179], v[168:171], v[72:75]
	v_mfma_f32_16x16x32_bf16 v[64:67], v[200:203], v[168:171], v[64:67]
	v_mfma_f32_16x16x32_bf16 v[120:123], v[196:199], v[148:151], v[120:123]
	v_mfma_f32_16x16x32_bf16 v[112:115], v[204:207], v[148:151], v[112:115]
	v_mfma_f32_16x16x32_bf16 v[104:107], v[196:199], v[156:159], v[104:107]
	v_mfma_f32_16x16x32_bf16 v[96:99], v[204:207], v[156:159], v[96:99]
	v_mfma_f32_16x16x32_bf16 v[88:91], v[196:199], v[164:167], v[88:91]
	v_mfma_f32_16x16x32_bf16 v[80:83], v[204:207], v[164:167], v[80:83]
	v_mfma_f32_16x16x32_bf16 v[72:75], v[196:199], v[172:175], v[72:75]
	v_mfma_f32_16x16x32_bf16 v[64:67], v[204:207], v[172:175], v[64:67]
	s_mov_b32 m0, s8
	v_lshl_add_u64 v[208:209], v[212:213], 0, s[96:97]
	s_barrier
	ds_read_b128 v[144:147], v239 offset:49152
	ds_read_b128 v[148:151], v239 offset:50176
	ds_read_b128 v[152:155], v239 offset:51200
	ds_read_b128 v[156:159], v239 offset:52224
	ds_read_b128 v[160:163], v239 offset:53248
	ds_read_b128 v[164:167], v239 offset:54272
	ds_read_b128 v[168:171], v239 offset:55296
	ds_read_b128 v[172:175], v239 offset:56320
	global_load_lds_dwordx4 v[208:209], off
	v_lshl_add_u64 v[208:209], v[214:215], 0, s[96:97]
	s_mov_b32 m0, s9
	s_nop 0
	global_load_lds_dwordx4 v[208:209], off
	s_barrier
	s_waitcnt lgkmcnt(0)
	s_waitcnt lgkmcnt(0)
	v_mfma_f32_16x16x32_bf16 v[60:63], v[128:131], v[144:147], v[60:63]
	v_mfma_f32_16x16x32_bf16 v[52:55], v[136:139], v[144:147], v[52:55]
	v_mfma_f32_16x16x32_bf16 v[44:47], v[128:131], v[152:155], v[44:47]
	v_mfma_f32_16x16x32_bf16 v[36:39], v[136:139], v[152:155], v[36:39]
	v_mfma_f32_16x16x32_bf16 v[28:31], v[128:131], v[160:163], v[28:31]
	v_mfma_f32_16x16x32_bf16 v[20:23], v[136:139], v[160:163], v[20:23]
	v_mfma_f32_16x16x32_bf16 v[12:15], v[128:131], v[168:171], v[12:15]
	v_mfma_f32_16x16x32_bf16 v[4:7], v[136:139], v[168:171], v[4:7]
	v_mfma_f32_16x16x32_bf16 v[60:63], v[132:135], v[148:151], v[60:63]
	v_mfma_f32_16x16x32_bf16 v[52:55], v[140:143], v[148:151], v[52:55]
	v_mfma_f32_16x16x32_bf16 v[44:47], v[132:135], v[156:159], v[44:47]
	v_mfma_f32_16x16x32_bf16 v[36:39], v[140:143], v[156:159], v[36:39]
	v_mfma_f32_16x16x32_bf16 v[28:31], v[132:135], v[164:167], v[28:31]
	v_mfma_f32_16x16x32_bf16 v[20:23], v[140:143], v[164:167], v[20:23]
	v_mfma_f32_16x16x32_bf16 v[12:15], v[132:135], v[172:175], v[12:15]
	v_mfma_f32_16x16x32_bf16 v[4:7], v[140:143], v[172:175], v[4:7]
	s_barrier
	s_add_i32 s40, s40, s33
	v_lshl_add_u64 v[128:129], v[216:217], 0, s[96:97]
	s_mov_b32 m0, s40
	s_nop 0
	global_load_lds_dwordx4 v[128:129], off
	v_lshl_add_u64 v[128:129], v[218:219], 0, s[96:97]
	s_add_i32 m0, s40, 0x2000
	s_nop 0
	global_load_lds_dwordx4 v[128:129], off
	s_waitcnt vmcnt(6)
	s_barrier
	v_mfma_f32_16x16x32_bf16 v[56:59], v[176:179], v[144:147], v[56:59]
	v_mfma_f32_16x16x32_bf16 v[48:51], v[200:203], v[144:147], v[48:51]
	v_mfma_f32_16x16x32_bf16 v[40:43], v[176:179], v[152:155], v[40:43]
	v_mfma_f32_16x16x32_bf16 v[32:35], v[200:203], v[152:155], v[32:35]
	v_mfma_f32_16x16x32_bf16 v[24:27], v[176:179], v[160:163], v[24:27]
	v_mfma_f32_16x16x32_bf16 v[16:19], v[200:203], v[160:163], v[16:19]
	v_mfma_f32_16x16x32_bf16 v[8:11], v[176:179], v[168:171], v[8:11]
	v_mfma_f32_16x16x32_bf16 v[0:3], v[200:203], v[168:171], v[0:3]
	v_mfma_f32_16x16x32_bf16 v[56:59], v[196:199], v[148:151], v[56:59]
	v_mfma_f32_16x16x32_bf16 v[48:51], v[204:207], v[148:151], v[48:51]
	v_mfma_f32_16x16x32_bf16 v[40:43], v[196:199], v[156:159], v[40:43]
	v_mfma_f32_16x16x32_bf16 v[32:35], v[204:207], v[156:159], v[32:35]
	v_mfma_f32_16x16x32_bf16 v[24:27], v[196:199], v[164:167], v[24:27]
	v_mfma_f32_16x16x32_bf16 v[16:19], v[204:207], v[164:167], v[16:19]
	v_mfma_f32_16x16x32_bf16 v[8:11], v[196:199], v[172:175], v[8:11]
	v_mfma_f32_16x16x32_bf16 v[0:3], v[204:207], v[172:175], v[0:3]
	s_add_u32 s0, s0, 0x100
	s_addc_u32 s1, s1, 0
	s_add_u32 s70, s70, 0x100
	s_addc_u32 s71, s71, 0
	s_cmp_ge_u32 s72, s7
	s_mov_b32 s40, s72
	s_barrier
	s_cbranch_scc0 .LBB0_141
	v_lshl_add_u32 v196, s19, 8, v181
	s_cmp_lt_i32 s78, 2
	s_mov_b64 s[0:1], -1
	s_cbranch_scc1 .LBB0_223
	s_cmp_gt_i32 s78, 2
	s_cbranch_scc0 .LBB0_220
	s_lshl_b32 s0, s18, 8
	s_ashr_i32 s68, s18, 1
	s_and_b32 s0, s0, 0x100
	s_cmp_lt_i32 s68, 2
	v_or_b32_e32 v148, s0, v238
	s_cselect_b64 s[0:1], -1, 0
	s_lshl_b32 s40, s68, 9
	s_add_i32 s80, s40, 0xfffffc00
	v_readlane_b32 s48, v241, 0
	s_lshl_b64 s[70:71], s[80:81], 2
	v_readlane_b32 s62, v241, 14
	v_readlane_b32 s63, v241, 15
	s_add_u32 s69, s62, s70
	s_addc_u32 s80, s63, s71
	s_ashr_i32 s41, s40, 31
	v_readlane_b32 s58, v241, 10
	s_lshl_b64 s[40:41], s[40:41], 2
	v_readlane_b32 s59, v241, 11
	s_add_u32 s99, s58, s40
	s_mov_b32 s83, s82
	s_addc_u32 s82, s59, s41
	s_cmp_lt_i32 s68, 4
	s_cselect_b64 s[72:73], -1, 0
	s_cmp_gt_i32 s68, 3
	s_cselect_b64 s[70:71], -1, 0
	v_mov_b32_e32 v132, 0
	s_and_b64 vcc, exec, s[70:71]
	v_lshlrev_b32_e32 v136, 2, v148
	v_mov_b32_e32 v140, 0
	v_mov_b32_e32 v141, v132
	v_mov_b32_e32 v142, 0
	v_mov_b32_e32 v143, 0
	v_readlane_b32 s49, v241, 1
	v_readlane_b32 s50, v241, 2
	v_readlane_b32 s51, v241, 3
	v_readlane_b32 s52, v241, 4
	v_readlane_b32 s53, v241, 5
	v_readlane_b32 s54, v241, 6
	v_readlane_b32 s55, v241, 7
	v_readlane_b32 s56, v241, 8
	v_readlane_b32 s57, v241, 9
	v_readlane_b32 s60, v241, 12
	v_readlane_b32 s61, v241, 13
	s_cbranch_vccnz .LBB0_146
	s_and_b64 s[40:41], s[0:1], exec
	s_cselect_b32 s41, s82, s80
	s_cselect_b32 s40, s99, s69
	global_load_dwordx4 v[140:143], v136, s[40:41]

.LBB0_230:
	s_setprio 0
	s_barrier
